# post-scan fence trimmed to one vmcnt(0)+barrier (carry lines cannot be in L1); deferred weight conversion in attention slack; on-chip Z carry scan
# baseline (speedup 1.0000x reference)
; __device__ __forceinline__ unsigned cvt_pk_bf16(float lo, float hi) { unsigned r; asm volatile("v_cvt_pk_bf16_f32 %0, %1, %2" : "=v"(r) : "v"(lo), "v"(hi)); return r; }
; __device__ __forceinline__ void s5_carry(LAS unsigned char* lds, const Params& P, int j, int g, int dir) {
;     ...
;     if (tid < 64) {
;         const int pp = tid; const int idx = ((j * 2 + dir) * 64 + g) * 64 + pp;
;         const f32x2 a32 = *(const f32x2*)(P.ws + WS_A32 + (size_t)idx * 8); const float ar = a32.x, ai = a32.y;
;         float cr = 0.f, cim = 0.f;
;         bf16_t* up = U2 + (size_t)g * 256 * 768 + 512 + dir * 128 + pp;
;         for (int s = 0; s < 256; ++s) {
;             const int n = dir ? (255 - s) : s;
;             up[(size_t)n * 768] = (bf16_t)(cvt_pk_bf16(cr, 0.f) & 0xffffu); up[(size_t)n * 768 + 64] = (bf16_t)(cvt_pk_bf16(cim, 0.f) & 0xffffu);
;             const float zr = zl[n * 128 + pp], zi = zl[n * 128 + 64 + pp];
;             const float nr = ar * cr - ai * cim + zr, ni = ar * cim + ai * cr + zi; cr = nr; cim = ni;
;         }
.Lcarry_loop1:
	s_waitcnt lgkmcnt(0)
	ds_read_b32 v186, v150 offset:8320
	ds_read_b32 v187, v150 offset:8576
	ds_read_b32 v188, v150 offset:9360
	ds_read_b32 v189, v150 offset:9616
	ds_read_b32 v190, v150 offset:10400
	ds_read_b32 v191, v150 offset:10656
	ds_read_b32 v192, v150 offset:11440
	ds_read_b32 v193, v150 offset:11696
	ds_read_b32 v194, v150 offset:12480
	ds_read_b32 v195, v150 offset:12736
	ds_read_b32 v196, v150 offset:13520
	ds_read_b32 v197, v150 offset:13776
	ds_read_b32 v198, v150 offset:14560
	ds_read_b32 v199, v150 offset:14816
	ds_read_b32 v210, v150 offset:15600
	ds_read_b32 v211, v150 offset:15856
	v_cvt_pk_bf16_f32 v144, v142, v143
	global_store_short v141, v144, s[34:35]
	global_store_short_d16_hi v141, v144, s[34:35] offset:128
	v_fma_f32 v146, v138, v142, v170
	v_fma_f32 v147, v138, v143, v171
	v_add_u32_e32 v141, s36, v141
	v_fma_f32 v148, -v139, v143, v146
	v_fma_f32 v149, v139, v142, v147
	v_cvt_pk_bf16_f32 v145, v148, v149
	global_store_short v141, v145, s[34:35]
	global_store_short_d16_hi v141, v145, s[34:35] offset:128
	v_fma_f32 v146, v138, v148, v172
	v_fma_f32 v147, v138, v149, v173
	v_add_u32_e32 v141, s36, v141
	v_fma_f32 v142, -v139, v149, v146
	v_fma_f32 v143, v139, v148, v147
	v_cvt_pk_bf16_f32 v144, v142, v143
	global_store_short v141, v144, s[34:35]
	global_store_short_d16_hi v141, v144, s[34:35] offset:128
	v_fma_f32 v146, v138, v142, v174
	v_fma_f32 v147, v138, v143, v175
	v_add_u32_e32 v141, s36, v141
	v_fma_f32 v148, -v139, v143, v146
	v_fma_f32 v149, v139, v142, v147
	v_cvt_pk_bf16_f32 v145, v148, v149
	global_store_short v141, v145, s[34:35]
	global_store_short_d16_hi v141, v145, s[34:35] offset:128
	v_fma_f32 v146, v138, v148, v176
	v_fma_f32 v147, v138, v149, v177
	v_add_u32_e32 v141, s36, v141
	v_fma_f32 v142, -v139, v149, v146
	v_fma_f32 v143, v139, v148, v147
	v_cvt_pk_bf16_f32 v144, v142, v143
	global_store_short v141, v144, s[34:35]
	global_store_short_d16_hi v141, v144, s[34:35] offset:128
	v_fma_f32 v146, v138, v142, v178
	v_fma_f32 v147, v138, v143, v179
	v_add_u32_e32 v141, s36, v141
	v_fma_f32 v148, -v139, v143, v146
	v_fma_f32 v149, v139, v142, v147
	v_cvt_pk_bf16_f32 v145, v148, v149
	global_store_short v141, v145, s[34:35]
	global_store_short_d16_hi v141, v145, s[34:35] offset:128
	v_fma_f32 v146, v138, v148, v180
	v_fma_f32 v147, v138, v149, v181
	v_add_u32_e32 v141, s36, v141
	v_fma_f32 v142, -v139, v149, v146
	v_fma_f32 v143, v139, v148, v147
	v_cvt_pk_bf16_f32 v144, v142, v143
	global_store_short v141, v144, s[34:35]
	global_store_short_d16_hi v141, v144, s[34:35] offset:128
	v_fma_f32 v146, v138, v142, v182
	v_fma_f32 v147, v138, v143, v183
	v_add_u32_e32 v141, s36, v141
	v_fma_f32 v148, -v139, v143, v146
	v_fma_f32 v149, v139, v142, v147
	v_cvt_pk_bf16_f32 v145, v148, v149
	global_store_short v141, v145, s[34:35]
	global_store_short_d16_hi v141, v145, s[34:35] offset:128
	v_fma_f32 v146, v138, v148, v184
	v_fma_f32 v147, v138, v149, v185
	v_add_u32_e32 v141, s36, v141
	v_fma_f32 v142, -v139, v149, v146
	v_fma_f32 v143, v139, v148, v147
	s_waitcnt lgkmcnt(0)
	ds_read_b32 v170, v150 offset:16640
	ds_read_b32 v171, v150 offset:16896
	ds_read_b32 v172, v150 offset:17680
	ds_read_b32 v173, v150 offset:17936
	ds_read_b32 v174, v150 offset:18720
	ds_read_b32 v175, v150 offset:18976
	ds_read_b32 v176, v150 offset:19760
	ds_read_b32 v177, v150 offset:20016
	ds_read_b32 v178, v150 offset:20800
	ds_read_b32 v179, v150 offset:21056
	ds_read_b32 v180, v150 offset:21840
	ds_read_b32 v181, v150 offset:22096
	ds_read_b32 v182, v150 offset:22880
	ds_read_b32 v183, v150 offset:23136
	ds_read_b32 v184, v150 offset:23920
	ds_read_b32 v185, v150 offset:24176
	v_cvt_pk_bf16_f32 v144, v142, v143
	global_store_short v141, v144, s[34:35]
	global_store_short_d16_hi v141, v144, s[34:35] offset:128
	v_fma_f32 v146, v138, v142, v186
	v_fma_f32 v147, v138, v143, v187
	v_add_u32_e32 v141, s36, v141
	v_fma_f32 v148, -v139, v143, v146
	v_fma_f32 v149, v139, v142, v147
	v_cvt_pk_bf16_f32 v145, v148, v149
	global_store_short v141, v145, s[34:35]
	global_store_short_d16_hi v141, v145, s[34:35] offset:128
	v_fma_f32 v146, v138, v148, v188
	v_fma_f32 v147, v138, v149, v189
	v_add_u32_e32 v141, s36, v141
	v_fma_f32 v142, -v139, v149, v146
	v_fma_f32 v143, v139, v148, v147
	v_cvt_pk_bf16_f32 v144, v142, v143
	global_store_short v141, v144, s[34:35]
	global_store_short_d16_hi v141, v144, s[34:35] offset:128
	v_fma_f32 v146, v138, v142, v190
	v_fma_f32 v147, v138, v143, v191
	v_add_u32_e32 v141, s36, v141
	v_fma_f32 v148, -v139, v143, v146
	v_fma_f32 v149, v139, v142, v147
	v_cvt_pk_bf16_f32 v145, v148, v149
	global_store_short v141, v145, s[34:35]
	global_store_short_d16_hi v141, v145, s[34:35] offset:128
	v_fma_f32 v146, v138, v148, v192
	v_fma_f32 v147, v138, v149, v193
	v_add_u32_e32 v141, s36, v141
	v_fma_f32 v142, -v139, v149, v146
	v_fma_f32 v143, v139, v148, v147
	v_cvt_pk_bf16_f32 v144, v142, v143
	global_store_short v141, v144, s[34:35]
	global_store_short_d16_hi v141, v144, s[34:35] offset:128
	v_fma_f32 v146, v138, v142, v194
	v_fma_f32 v147, v138, v143, v195
	v_add_u32_e32 v141, s36, v141
	v_fma_f32 v148, -v139, v143, v146
	v_fma_f32 v149, v139, v142, v147
	v_cvt_pk_bf16_f32 v145, v148, v149
	global_store_short v141, v145, s[34:35]
	global_store_short_d16_hi v141, v145, s[34:35] offset:128
	v_fma_f32 v146, v138, v148, v196
	v_fma_f32 v147, v138, v149, v197
	v_add_u32_e32 v141, s36, v141
	v_fma_f32 v142, -v139, v149, v146
	v_fma_f32 v143, v139, v148, v147
	v_cvt_pk_bf16_f32 v144, v142, v143
	global_store_short v141, v144, s[34:35]
	global_store_short_d16_hi v141, v144, s[34:35] offset:128
	v_fma_f32 v146, v138, v142, v198
	v_fma_f32 v147, v138, v143, v199
	v_add_u32_e32 v141, s36, v141
	v_fma_f32 v148, -v139, v143, v146
	v_fma_f32 v149, v139, v142, v147
	v_cvt_pk_bf16_f32 v145, v148, v149
	global_store_short v141, v145, s[34:35]
	global_store_short_d16_hi v141, v145, s[34:35] offset:128
	v_fma_f32 v146, v138, v148, v210
	v_fma_f32 v147, v138, v149, v211
	v_add_u32_e32 v141, s36, v141
	v_fma_f32 v142, -v139, v149, v146
	v_fma_f32 v143, v139, v148, v147
	v_add_u32_e32 v150, 0x4100, v150
	s_add_i32 s12, s12, 1
	s_cmp_lt_u32 s12, 8
	s_cbranch_scc1 .Lcarry_loop1
	s_waitcnt lgkmcnt(0)
	s_waitcnt vmcnt(0)

; #define PG8_STAGE(bufoff, gbase, voff) do { _Pragma("unroll") for (int _i = 0; _i < 2; ++_i) \
;         __builtin_amdgcn_global_load_lds((const unsigned*)((const char*)(gbase) + (voff)[_i]), (LAS unsigned*)(lds + (bufoff) + ldsw + _i * 8192), 16, 0, 0); } while (0)
; template <class Epi, class Sched>
; __device__ __forceinline__ void gemm_phase(LAS unsigned char* lds, const Gemm g, const Sched& S, const Epi& E) {
;     ...
;     const int wid = __builtin_amdgcn_readfirstlane(tid >> 6), lane = tid & 63, wr = wid >> 2, wc = wid & 3, fr = lane & 15, fq = lane >> 4;
;     const int K = g.K, nt = K / BK;
;     unsigned voffA[2], voffB[2];
; #pragma unroll
;     for (int i = 0; i < 2; ++i) { int R, C; stage_rc(tid * 16 + i * 8192, R, C); const int Rb = Epi::PERM ? ((R & ~31) + perm32(R & 31)) : R;
;         voffA[i] = (unsigned)(R * g.lda + C) * 2u; voffB[i] = (unsigned)(Rb * g.ldb + C) * 2u; }
;     const size_t kstep = (size_t)(BK * 2);
;     const size_t hstepA = (size_t)HALF * g.lda * 2, hstepB = (size_t)HALF * g.ldb * 2;
;     const size_t tstepA = 2 * hstepA, tstepB = 2 * hstepB;
;     const unsigned ldsw = (unsigned)wid * 1024u;
;     const int aoff = lds_byte(wr * 64 + fr, fq * 8), boff = lds_byte(wc * 32 + fr, fq * 8);
;     ...
;     Unit cur, nxt; int ui = 0;
;     if (!S.next(0, cur)) return;
;     f32x4 acc[2][2][4][2];
; #pragma unroll
;     for (int a = 0; a < 2; ++a)
; #pragma unroll
;         for (int b = 0; b < 2; ++b)
; #pragma unroll
;             for (int m = 0; m < 4; ++m)
; #pragma unroll
;                 for (int n = 0; n < 2; ++n) acc[a][b][m][n] = (f32x4){0.f, 0.f, 0.f, 0.f};
;     bf16x8 At[4][2], B0[2][2], B1[2][2];
;     const char* cA = (const char*)g.A + (size_t)cur.pm * tstepA; const char* cB = (const char*)g.Bt + (size_t)cur.pn * tstepB;
;     PG8_STAGE(PG8_SB(0, 0), cB, voffB); PG8_STAGE(PG8_SA(0, 0), cA, voffA); PG8_STAGE(PG8_SB(0, 1), cB + hstepB, voffB); PG8_STAGE(PG8_SA(0, 1), cA + hstepA, voffA);
; __global__ void __launch_bounds__(NTHR) hybrid_encoder_fwd(Params P) {
;     ...
;                     asm volatile("s_waitcnt vmcnt(0)" ::: "memory"); __syncthreads();
;                     __builtin_amdgcn_fence(__ATOMIC_ACQUIRE, "agent"); asm volatile("s_waitcnt vmcnt(0)" ::: "memory"); __syncthreads();
;                     Gemm g3; g3.A = U2; g3.Bt = (const bf16_t*)(ws + WS_B3 + j * SZ_B3); g3.lda = 768; g3.ldb = 768; g3.K = 768;
.LBB0_591:
	v_mov_b32_e32 v6, v200
	s_mul_i32 s1, s70, 0x3000000
	v_ashrrev_i32_e32 v2, 31, v6
	v_lshrrev_b32_e32 v2, 26, v2
	v_add_u32_e32 v2, v6, v2
	v_ashrrev_i32_e32 v7, 6, v2
	v_bfe_i32 v2, v6, 27, 1
	v_lshlrev_b32_e32 v1, 4, v6
	v_lshrrev_b32_e32 v2, 22, v2
	v_add_u32_e32 v2, v1, v2
	v_and_b32_e32 v2, 0xfffffc00, v2
	v_sub_u32_e32 v2, v1, v2
	v_lshrrev_b32_e32 v3, 4, v2
	v_bitop3_b32 v2, v3, v2, 32 bitop3:0x6c
	v_ashrrev_i32_e32 v4, 31, v2
	v_lshrrev_b32_e32 v4, 26, v4
	v_lshlrev_b32_e32 v3, 3, v7
	v_add_u32_e32 v4, v2, v4
	v_readlane_b32 s12, v254, 30
	v_and_b32_e32 v3, -16, v3
	v_ashrrev_i32_e32 v9, 6, v4
	v_and_b32_e32 v4, 0xc0, v4
	s_mul_hi_u32 s0, s70, 0x3000000
	s_add_u32 s21, s12, s1
	v_readlane_b32 s1, v254, 31
	v_add_u32_e32 v3, v9, v3
	v_lshlrev_b32_e32 v5, 5, v7
	v_sub_u32_e32 v2, v2, v4
	s_addc_u32 s20, s1, s0
	v_and_b32_e32 v8, 32, v5
	v_ashrrev_i16_sdwa v2, v204, sext(v2) dst_sel:DWORD dst_unused:UNUSED_PAD src0_sel:DWORD src1_sel:BYTE_0
	v_lshlrev_b32_e32 v4, 1, v3
	v_lshrrev_b32_e32 v5, 2, v3
	v_and_b32_e32 v11, 3, v9
	s_mov_b32 s1, 0xffffe0
	v_bfe_i32 v10, v2, 0, 16
	v_and_b32_e32 v4, 24, v4
	v_and_b32_e32 v5, 4, v5
	v_and_or_b32 v11, v3, s1, v11
	s_movk_i32 s0, 0x300
	v_add_u32_e32 v2, v8, v10
	v_or3_b32 v4, v11, v5, v4
	v_mul_lo_u32 v3, v3, s0
	v_add_lshl_u32 v130, v2, v3, 1
	v_mul_u32_u24_e32 v3, 0x300, v4
	v_add_u32_e32 v1, 0x2000, v1
	v_add_lshl_u32 v132, v3, v2, 1
	v_ashrrev_i32_e32 v2, 31, v1
	v_lshrrev_b32_e32 v2, 22, v2
	v_add_u32_e32 v2, v1, v2
	v_ashrrev_i32_e32 v11, 10, v2
	v_mul_i32_i24_e32 v2, 0x400, v11
	v_sub_u32_e32 v1, v1, v2
	v_lshrrev_b32_e32 v2, 4, v1
	v_bitop3_b32 v1, v2, v1, 32 bitop3:0x6c
	v_ashrrev_i32_e32 v3, 31, v1
	v_lshrrev_b32_e32 v3, 26, v3
	v_lshlrev_b32_e32 v2, 3, v11
	v_add_u32_e32 v3, v1, v3
	v_readfirstlane_b32 s12, v6
	v_and_b32_e32 v2, -16, v2
	v_ashrrev_i32_e32 v13, 6, v3
	v_and_b32_e32 v3, 0xc0, v3
	v_add_u32_e32 v2, v13, v2
	v_lshlrev_b32_e32 v4, 5, v11
	v_sub_u32_e32 v1, v1, v3
	v_and_b32_e32 v5, 3, v13
	s_ashr_i32 s28, s12, 6
	s_ashr_i32 s26, s12, 8
	v_and_b32_e32 v12, 32, v4
	v_ashrrev_i16_sdwa v1, v204, sext(v1) dst_sel:DWORD dst_unused:UNUSED_PAD src0_sel:DWORD src1_sel:BYTE_0
	v_lshlrev_b32_e32 v3, 1, v2
	v_lshrrev_b32_e32 v4, 2, v2
	v_and_or_b32 v5, v2, s1, v5
	v_mul_lo_u32 v2, v2, s0
	s_lshl_b32 s13, s28, 10
	s_mul_i32 s0, s2, 0xc0000
	v_readlane_b32 s1, v252, 17
	v_bfe_i32 v14, v1, 0, 16
	v_and_b32_e32 v3, 24, v3
	v_and_b32_e32 v4, 4, v4
	s_add_u32 s0, s21, s0
	s_mul_hi_i32 s1, s1, 0x60000
	v_add_u32_e32 v1, v12, v14
	v_or3_b32 v3, v5, v4, v3
	s_addc_u32 s1, s20, s1
	s_add_i32 s34, s13, 0
	v_add_lshl_u32 v134, v1, v2, 1
	v_mul_u32_u24_e32 v2, 0x300, v3
	s_add_i32 m0, s34, 0x10000
	v_add_lshl_u32 v136, v2, v1, 1
	global_load_lds_dwordx4 v132, s[0:1]
	s_add_i32 m0, s34, 0x12000
	v_readlane_b32 s36, v254, 13
	global_load_lds_dwordx4 v136, s[0:1]
	s_mov_b32 m0, s34
	v_readlane_b32 s37, v254, 14
	s_add_i32 s35, s34, 0x2000
	v_mov_b32_e32 v133, v0
	v_mov_b32_e32 v137, v0
	v_lshl_add_u64 v[2:3], s[0:1], 0, v[132:133]
	v_lshl_add_u64 v[4:5], s[0:1], 0, v[136:137]
	global_load_lds_dwordx4 v130, s[36:37]
	s_mov_b32 m0, s35
	s_nop 0
	global_load_lds_dwordx4 v134, s[36:37]
	s_add_u32 s36, s0, 0x30000
	s_addc_u32 s37, s1, 0
	s_add_i32 m0, s34, 0x14000
	s_add_i32 s48, s34, 0x4000
	global_load_lds_dwordx4 v132, s[36:37]
	s_add_i32 m0, s34, 0x16000
	s_add_i32 s49, s34, 0x6000
	global_load_lds_dwordx4 v136, s[36:37]
	v_readlane_b32 s36, v254, 15
	s_mov_b32 m0, s48
	v_readlane_b32 s37, v254, 16
	s_cmp_lg_u32 s26, 1
	s_nop 3
	global_load_lds_dwordx4 v130, s[36:37]
	s_mov_b32 m0, s49
	s_nop 0
	global_load_lds_dwordx4 v134, s[36:37]
	s_cbranch_scc1 .LBB0_593
	s_barrier
